# fa3 + phase0 w_in transpose: both tile loads issued before first wait
# speedup vs baseline: 1.5143x; 1.0090x over previous
; DI int opaque_tid() { int t = threadIdx.x; asm volatile("" : "+v"(t)); return t; }
; DI int win_srccol(int j) {
;     if (j < 5120) return j;
;     if (j < 10752) return j + 32;
;     if (j < 14848) return j + 80;
;     if (j < 14880) return j - 14848 + 5120;
;     if (j < 14928) return j - 14880 + 10784;
;     return -1;
; }
; DI void transpose_tile(const float* src, int ldsrc, bf16_t* dst, int lddst, int k0, int n0, int mode, const float* rowscale, float* tile) {
;     const int tid = opaque_tid();
;     {
;         const int r = tid >> 4, c4 = (tid & 15) * 4;
; #pragma unroll
;         for (int q = 0; q < 2; ++q) {
;             const int rr = r + 32 * q; const int jd = n0 + c4; const int js = mode ? win_srccol(jd) : jd;
;             f32x4 v = {0.f, 0.f, 0.f, 0.f};
;             if (js >= 0) v = *(const f32x4*)(src + (size_t)(k0 + rr) * ldsrc + js);
;             if (rowscale) { const float sc = rowscale[k0 + rr]; v = v * sc; }
;             tile[rr * 65 + c4 + 0] = v[0]; tile[rr * 65 + c4 + 1] = v[1]; tile[rr * 65 + c4 + 2] = v[2]; tile[rr * 65 + c4 + 3] = v[3];
;         }
.LBB0_48:
	s_andn2_b64 vcc, exec, s[8:9]
	s_cbranch_vccnz .LBB0_25
	v_mov_b32_e32 v26, v215
	s_and_b32 s78, s85, 0xffffffc0
	v_lshlrev_b32_e32 v0, 2, v26
	v_and_b32_e32 v1, 60, v0
	s_and_b32 s14, s83, 0x7c0
	v_or_b32_e32 v0, s78, v1
	s_cmpk_lt_u32 s85, 0x2a00
	v_add_u32_e32 v3, 0xfffff000, v0
	v_cmp_gt_u32_e64 s[8:9], s94, v0
	s_cselect_b64 vcc, -1, 0
	s_cmpk_lt_u32 s85, 0x3a00
	v_cndmask_b32_e64 v3, -1, v3, s[8:9]
	v_add_u32_e32 v4, 0xffffda00, v0
	v_cmp_gt_u32_e64 s[8:9], s93, v0
	v_add_u32_e32 v5, 0x50, v0
	v_add_u32_e32 v2, 32, v0
	v_cndmask_b32_e64 v3, v3, v4, s[8:9]
	s_cselect_b64 s[8:9], -1, 0
	v_cndmask_b32_e64 v3, v3, v5, s[8:9]
	v_cndmask_b32_e32 v2, v3, v2, vcc
	v_cmp_gt_i32_e32 vcc, s92, v0
	v_ashrrev_i32_e32 v27, 4, v26
	v_cndmask_b32_e32 v24, v2, v0, vcc
	v_cmp_lt_i32_e32 vcc, -1, v24
	v_lshl_add_u32 v1, v1, 2, 0
	v_mul_lo_u32 v28, v27, s91
	v_add_u32_e32 v28, v1, v28
	v_mov_b32_e32 v112, 0
	v_mov_b32_e32 v113, 0
	v_mov_b32_e32 v114, 0
	v_mov_b32_e32 v115, 0
	v_mov_b32_e32 v0, 0
	v_mov_b32_e32 v1, 0
	v_mov_b32_e32 v2, 0
	v_mov_b32_e32 v3, 0
	s_and_saveexec_b64 s[8:9], vcc
	s_cbranch_execz .Lp0_win_noload
	v_add_u32_e32 v4, s14, v27
	v_mov_b64_e32 v[116:117], s[16:17]
	v_mad_i64_i32 v[116:117], s[0:1], v4, s95, v[116:117]
	v_lshl_add_u64 v[116:117], v[24:25], 2, v[116:117]
	global_load_dwordx4 v[112:115], v[116:117], off
	v_add3_u32 v4, v27, s14, 32
	v_mov_b64_e32 v[118:119], s[16:17]
	v_mad_i64_i32 v[118:119], s[0:1], v4, s95, v[118:119]
	v_lshl_add_u64 v[118:119], v[24:25], 2, v[118:119]
	global_load_dwordx4 v[0:3], v[118:119], off
.Lp0_win_noload:
	s_or_b64 exec, exec, s[8:9]
	s_waitcnt vmcnt(1)
	ds_write2_b32 v28, v112, v113 offset1:1
	ds_write2_b32 v28, v114, v115 offset0:2 offset1:3
	s_branch .LBB0_24
